# v26 + kmean item: all 16 row loads of an iteration issued before the first wait (was 12, wait, 4)
# baseline (speedup 1.0000x reference)
.LBB0_1072:
	v_lshl_add_u64 v[4:5], v[2:3], 0, s[0:1]
	v_add_co_u32_e32 v6, vcc, 0x4500000, v4
	s_add_u32 s0, s0, 0xc000
	s_nop 0
	v_addc_co_u32_e32 v7, vcc, 0, v5, vcc
	v_add_co_u32_e32 v8, vcc, 0x4501000, v4
	s_addc_u32 s1, s1, 0
	s_nop 0
	v_addc_co_u32_e32 v9, vcc, 0, v5, vcc
	v_add_co_u32_e32 v10, vcc, 0x4502000, v4
	global_load_ushort v12, v[6:7], off offset:2560
	global_load_ushort v13, v[8:9], off offset:1536
	v_addc_co_u32_e32 v11, vcc, 0, v5, vcc
	v_add_co_u32_e32 v6, vcc, 0x4503000, v4
	s_cmp_eq_u32 s0, 0x30000
	s_nop 0
	v_addc_co_u32_e32 v7, vcc, 0, v5, vcc
	v_add_co_u32_e32 v8, vcc, 0x4504000, v4
	global_load_ushort v14, v[10:11], off offset:512
	global_load_ushort v15, v[10:11], off offset:3584
	global_load_ushort v16, v[6:7], off offset:2560
	v_addc_co_u32_e32 v9, vcc, 0, v5, vcc
	v_add_co_u32_e32 v6, vcc, 0x4505000, v4
	s_nop 1
	v_addc_co_u32_e32 v7, vcc, 0, v5, vcc
	v_add_co_u32_e32 v10, vcc, 0x4506000, v4
	global_load_ushort v17, v[8:9], off offset:1536
	global_load_ushort v18, v[6:7], off offset:512
	global_load_ushort v19, v[6:7], off offset:3584
	v_addc_co_u32_e32 v11, vcc, 0, v5, vcc
	v_add_co_u32_e32 v6, vcc, 0x4507000, v4
	global_load_ushort v20, v[10:11], off offset:2560
	s_nop 0
	v_addc_co_u32_e32 v7, vcc, 0, v5, vcc
	v_add_co_u32_e32 v8, vcc, 0x4508000, v4
	s_nop 1
	v_addc_co_u32_e32 v9, vcc, 0, v5, vcc
	v_add_co_u32_e32 v10, vcc, 0x4509000, v4
	global_load_ushort v21, v[6:7], off offset:1536
	global_load_ushort v22, v[8:9], off offset:512
	s_nop 0
	global_load_ushort v8, v[8:9], off offset:3584
	v_addc_co_u32_e32 v11, vcc, 0, v5, vcc
	v_add_co_u32_e32 v6, vcc, 0x450a000, v4
	s_nop 1
	v_addc_co_u32_e32 v7, vcc, 0, v5, vcc
	v_add_co_u32_e32 v4, vcc, 0x450b000, v4
	global_load_ushort v9, v[10:11], off offset:2560
	s_nop 0
	global_load_ushort v6, v[6:7], off offset:1536
	v_addc_co_u32_e32 v5, vcc, 0, v5, vcc
	global_load_ushort v7, v[4:5], off offset:512
	s_nop 0
	global_load_ushort v4, v[4:5], off offset:3584
	s_waitcnt vmcnt(4)
	v_lshlrev_b32_e32 v8, 16, v8
	v_lshlrev_b32_e32 v5, 16, v12
	v_add_f32_e32 v1, v1, v5
	v_lshlrev_b32_e32 v5, 16, v13
	v_add_f32_e32 v1, v1, v5
	v_lshlrev_b32_e32 v5, 16, v14
	v_lshlrev_b32_e32 v10, 16, v15
	v_add_f32_e32 v1, v1, v5
	v_lshlrev_b32_e32 v5, 16, v16
	v_add_f32_e32 v1, v1, v10
	v_lshlrev_b32_e32 v10, 16, v17
	v_add_f32_e32 v1, v1, v5
	v_lshlrev_b32_e32 v5, 16, v18
	v_add_f32_e32 v1, v1, v10
	v_lshlrev_b32_e32 v11, 16, v19
	v_add_f32_e32 v1, v1, v5
	v_lshlrev_b32_e32 v10, 16, v20
	v_add_f32_e32 v1, v1, v11
	v_lshlrev_b32_e32 v5, 16, v21
	v_add_f32_e32 v1, v1, v10
	v_lshlrev_b32_e32 v11, 16, v22
	v_add_f32_e32 v1, v1, v5
	v_add_f32_e32 v1, v1, v11
	v_add_f32_e32 v1, v1, v8
	s_waitcnt vmcnt(3)
	v_lshlrev_b32_e32 v9, 16, v9
	s_waitcnt vmcnt(2)
	v_lshlrev_b32_e32 v5, 16, v6
	v_add_f32_e32 v1, v1, v9
	s_waitcnt vmcnt(1)
	v_lshlrev_b32_e32 v6, 16, v7
	v_add_f32_e32 v1, v1, v5
	s_waitcnt vmcnt(0)
	v_lshlrev_b32_e32 v4, 16, v4
	v_add_f32_e32 v1, v1, v6
	v_add_f32_e32 v1, v1, v4
	s_cbranch_scc0 .LBB0_1072
	v_lshlrev_b32_e32 v2, 2, v0
	v_cmp_gt_i32_e32 vcc, 64, v0
	s_barrier
	ds_write_b32 v2, v1
	s_waitcnt lgkmcnt(0)
	s_barrier
	s_and_saveexec_b64 s[0:1], vcc
	s_cbranch_execz .LBB0_1075
	ds_read2st64_b32 v[4:5], v2 offset1:1
	ds_read2st64_b32 v[2:3], v2 offset0:2 offset1:3
	s_lshl_b32 s2, s37, 6
	s_add_i32 s2, s2, 0xfffc0000
	s_lshl_b64 s[6:7], s[2:3], 1
	s_waitcnt lgkmcnt(1)
	v_add_f32_e32 v4, v4, v5
	s_waitcnt lgkmcnt(0)
	v_add_f32_e32 v2, v4, v2
	v_add_f32_e32 v2, v2, v3
	s_add_u32 s6, s8, s6
	v_ashrrev_i32_e32 v1, 31, v0
	v_mul_f32_e32 v2, 0x3b800000, v2
	s_addc_u32 s7, s9, s7
	v_cvt_pk_bf16_f32 v2, v2, s0
	v_lshl_add_u64 v[0:1], v[0:1], 1, s[6:7]
	global_store_short v[0:1], v2, off
